# attention main loop: 8 V fragments prefetched per half-step, rescale block out of line, -m_run as MFMA C operand (one MFMA less), rescale test on half-row maxima
# speedup vs baseline: 1.0100x; 1.0100x over previous
; #define LAS __attribute__((address_space(3)))
; __device__ __forceinline__ unsigned f2bf(float f) { unsigned u = __builtin_bit_cast(unsigned, f); return (u + 0x7fffu + ((u >> 16) & 1u)) >> 16; }
; __device__ __forceinline__ float max_x32(float x) { float a = x, b = x; swap_x32(a, b); return fmaxf(a, b); }
; #define MFMA32(a, b, c) __builtin_amdgcn_mfma_f32_32x32x16_bf16((a), (b), (c), 0, 0, 0)
; template <bool TAIL> ...
;     if (TAIL) {
;         const int kb = key0 + 4 * hi;
; #pragma unroll
;         for (int i = 0; i < 16; ++i) { const int key = kb + (i & 3) + 8 * (i >> 2); if (key > qrow) Sc[i] = -1e30f; }
;     }
;     float mloc = fmaxf(Sc[0], Sc[1]);
; #pragma unroll
;     for (int i = 2; i < 16; ++i) mloc = fmaxf(mloc, Sc[i]);
;     mloc = max_x32(mloc);
;     const bool first = (key0 == 0);
;     if (__any(mloc > 8.f) || first) {
;         const float m_new = (mloc > 8.f || first) ? __builtin_bit_cast(float, f2bf(m_run + mloc) << 16) : m_run;
;         const float delta = m_new - m_run, alpha = __builtin_amdgcn_exp2f(-delta);
;         l_run *= alpha;
; #pragma unroll
;         for (int d = 0; d < 4; ++d)
; #pragma unroll
;             for (int i = 0; i < 16; ++i) O[d][i] *= alpha;
; #pragma unroll
;         for (int i = 0; i < 16; ++i) Sc[i] -= delta;
;         m_run = m_new;
;         mfrag[0] = hi ? (short)0 : (short)(f2bf(-m_new));
;     }
; #pragma unroll
;     for (int i = 0; i < 16; ++i) Sn[i] = 0.f;
;     Sn = MFMA32(onefrag, mfrag, Sn);
; #pragma unroll
;     for (int ks = 0; ks < 4; ++ks) {
;         const bf16x8 a0 = *(LAS const bf16x8*)(Kn + ka + (((2 * ks + hi) ^ kx) << 4));
;         Sn = MFMA32(a0, qf[ks], Sn);
;     }
.LBB0_224:
	s_and_b64 vcc, exec, s[4:5]
	s_cbranch_vccz .LBB0_243
	v_add3_u32 v152, s21, v223, v225
	v_add3_u32 v153, s21, v223, v226
	v_add3_u32 v154, s21, v223, v227
	v_add3_u32 v155, s21, v223, v228
	ds_read_b128 v[240:243], v152 offset:4096
	ds_read_b128 v[244:247], v153 offset:4096
	ds_read_b128 v[248:251], v154 offset:4096
	ds_read_b128 v[204:207], v155 offset:4096
	v_add3_u32 v156, s19, v213, v229
	v_add3_u32 v157, s19, v213, v230
	v_add3_u32 v158, s19, v213, v231
	v_add3_u32 v159, s19, v213, v232
	v_readfirstlane_b32 s23, v212
	v_xor_b32_e32 v120, 0x80000000, v238
	v_xor_b32_e32 v121, 0x80000000, v238
	v_xor_b32_e32 v122, 0x80000000, v238
	v_xor_b32_e32 v123, 0x80000000, v238
	v_xor_b32_e32 v124, 0x80000000, v238
	v_xor_b32_e32 v125, 0x80000000, v238
	v_xor_b32_e32 v126, 0x80000000, v238
	v_xor_b32_e32 v127, 0x80000000, v238
	v_xor_b32_e32 v128, 0x80000000, v238
	v_xor_b32_e32 v129, 0x80000000, v238
	v_xor_b32_e32 v130, 0x80000000, v238
	v_xor_b32_e32 v131, 0x80000000, v238
	v_xor_b32_e32 v132, 0x80000000, v238
	v_xor_b32_e32 v133, 0x80000000, v238
	v_xor_b32_e32 v134, 0x80000000, v238
	v_xor_b32_e32 v135, 0x80000000, v238
	v_max3_f32 v166, v64, v65, v66
	v_max3_f32 v166, v166, v67, v68
	v_max3_f32 v166, v166, v69, v70
	v_max3_f32 v166, v166, v71, v72
	v_max3_f32 v166, v166, v73, v74
	v_max3_f32 v166, v166, v75, v76
	v_max3_f32 v166, v166, v77, v78
	v_max_f32_e32 v166, v166, v79
	v_mov_b32_e32 v239, v166
	s_nop 1
	v_permlane32_swap_b32 v166, v239
	s_nop 0
	v_max_f32_e32 v166, v166, v239
	v_cmp_lt_f32_e64 s[4:5], s92, v166
	s_cmp_eq_u32 s22, 0
	s_cselect_b64 s[14:15], -1, 0
	s_nop 0
	s_or_b64 s[14:15], s[14:15], s[4:5]
	s_cmp_eq_u64 s[14:15], 0
	s_cbranch_scc1 .Lda_entry_done
	v_mov_b32_e32 v136, v238
	s_and_saveexec_b64 s[4:5], s[14:15]
	v_add_f32_e32 v136, v238, v166
	v_bfe_u32 v137, v136, 16, 1
	v_add3_u32 v136, v136, v137, s93
	v_and_b32_e32 v136, 0xffff0000, v136
	s_or_b64 exec, exec, s[4:5]
	v_sub_f32_e32 v138, v136, v238
	v_xor_b32_e32 v137, 0x80000000, v136
	v_exp_f32_e64 v140, -v138
	v_mov_b32_e32 v120, v137
	v_mov_b32_e32 v121, v137
	v_mov_b32_e32 v122, v137
	v_mov_b32_e32 v123, v137
	v_mov_b32_e32 v124, v137
	v_mov_b32_e32 v125, v137
	v_mov_b32_e32 v126, v137
	v_mov_b32_e32 v127, v137
	v_mov_b32_e32 v128, v137
	v_mov_b32_e32 v129, v137
	v_mov_b32_e32 v130, v137
	v_mov_b32_e32 v131, v137
	v_mov_b32_e32 v132, v137
	v_mov_b32_e32 v133, v137
	v_mov_b32_e32 v134, v137
	v_mov_b32_e32 v135, v137
	v_pk_add_f32 v[64:65], v[64:65], v[138:139] op_sel_hi:[1,0] neg_lo:[0,1] neg_hi:[0,1]
	v_pk_add_f32 v[66:67], v[66:67], v[138:139] op_sel_hi:[1,0] neg_lo:[0,1] neg_hi:[0,1]
	v_pk_add_f32 v[68:69], v[68:69], v[138:139] op_sel_hi:[1,0] neg_lo:[0,1] neg_hi:[0,1]
	v_pk_add_f32 v[70:71], v[70:71], v[138:139] op_sel_hi:[1,0] neg_lo:[0,1] neg_hi:[0,1]
	v_pk_add_f32 v[72:73], v[72:73], v[138:139] op_sel_hi:[1,0] neg_lo:[0,1] neg_hi:[0,1]
	v_pk_add_f32 v[74:75], v[74:75], v[138:139] op_sel_hi:[1,0] neg_lo:[0,1] neg_hi:[0,1]
	v_pk_add_f32 v[76:77], v[76:77], v[138:139] op_sel_hi:[1,0] neg_lo:[0,1] neg_hi:[0,1]
	v_pk_add_f32 v[78:79], v[78:79], v[138:139] op_sel_hi:[1,0] neg_lo:[0,1] neg_hi:[0,1]
	v_bfe_u32 v142, v137, 16, 1
	v_add3_u32 v137, v137, v142, s93
	v_lshrrev_b32_e32 v137, 16, v137
	v_cndmask_b32_e64 v137, 0, v137, s[0:1]
	v_bfi_b32 v184, s94, v137, v184
	v_mul_f32_e32 v165, v165, v140
	v_pk_mul_f32 v[62:63], v[62:63], v[140:141] op_sel_hi:[1,0]
	v_pk_mul_f32 v[60:61], v[60:61], v[140:141] op_sel_hi:[1,0]
	v_pk_mul_f32 v[58:59], v[58:59], v[140:141] op_sel_hi:[1,0]
	v_pk_mul_f32 v[56:57], v[56:57], v[140:141] op_sel_hi:[1,0]
	v_pk_mul_f32 v[54:55], v[54:55], v[140:141] op_sel_hi:[1,0]
	v_pk_mul_f32 v[52:53], v[52:53], v[140:141] op_sel_hi:[1,0]
	v_pk_mul_f32 v[50:51], v[50:51], v[140:141] op_sel_hi:[1,0]
	v_pk_mul_f32 v[48:49], v[48:49], v[140:141] op_sel_hi:[1,0]
	v_pk_mul_f32 v[46:47], v[46:47], v[140:141] op_sel_hi:[1,0]
	v_pk_mul_f32 v[44:45], v[44:45], v[140:141] op_sel_hi:[1,0]
	v_pk_mul_f32 v[42:43], v[42:43], v[140:141] op_sel_hi:[1,0]
	v_pk_mul_f32 v[40:41], v[40:41], v[140:141] op_sel_hi:[1,0]
	v_pk_mul_f32 v[38:39], v[38:39], v[140:141] op_sel_hi:[1,0]
	v_pk_mul_f32 v[36:37], v[36:37], v[140:141] op_sel_hi:[1,0]
	v_pk_mul_f32 v[34:35], v[34:35], v[140:141] op_sel_hi:[1,0]
	v_pk_mul_f32 v[32:33], v[32:33], v[140:141] op_sel_hi:[1,0]
	v_pk_mul_f32 v[30:31], v[30:31], v[140:141] op_sel_hi:[1,0]
	v_pk_mul_f32 v[28:29], v[28:29], v[140:141] op_sel_hi:[1,0]
	v_pk_mul_f32 v[26:27], v[26:27], v[140:141] op_sel_hi:[1,0]
	v_pk_mul_f32 v[24:25], v[24:25], v[140:141] op_sel_hi:[1,0]
	v_pk_mul_f32 v[22:23], v[22:23], v[140:141] op_sel_hi:[1,0]
	v_pk_mul_f32 v[20:21], v[20:21], v[140:141] op_sel_hi:[1,0]
	v_pk_mul_f32 v[18:19], v[18:19], v[140:141] op_sel_hi:[1,0]
	v_pk_mul_f32 v[16:17], v[16:17], v[140:141] op_sel_hi:[1,0]
	v_pk_mul_f32 v[14:15], v[14:15], v[140:141] op_sel_hi:[1,0]
	v_pk_mul_f32 v[12:13], v[12:13], v[140:141] op_sel_hi:[1,0]
	v_pk_mul_f32 v[10:11], v[10:11], v[140:141] op_sel_hi:[1,0]
	v_pk_mul_f32 v[8:9], v[8:9], v[140:141] op_sel_hi:[1,0]
	v_pk_mul_f32 v[6:7], v[6:7], v[140:141] op_sel_hi:[1,0]
	v_pk_mul_f32 v[4:5], v[4:5], v[140:141] op_sel_hi:[1,0]
	v_pk_mul_f32 v[2:3], v[2:3], v[140:141] op_sel_hi:[1,0]
	v_pk_mul_f32 v[0:1], v[0:1], v[140:141] op_sel_hi:[1,0]
	v_mov_b32_e32 v238, v136

; #define LAS __attribute__((address_space(3)))
; __device__ __forceinline__ unsigned f2bf(float f) { unsigned u = __builtin_bit_cast(unsigned, f); return (u + 0x7fffu + ((u >> 16) & 1u)) >> 16; }
; __device__ __forceinline__ float max_x32(float x) { float a = x, b = x; swap_x32(a, b); return fmaxf(a, b); }
; #define MFMA32(a, b, c) __builtin_amdgcn_mfma_f32_32x32x16_bf16((a), (b), (c), 0, 0, 0)
; __device__ __forceinline__ s16x4 vtr(LAS const unsigned char* p) { return __builtin_bit_cast(s16x4, __builtin_amdgcn_ds_read_tr16_b64_v4i16((LAS v4i16_t*)p)); }
; template <bool TAIL> ...
;     ...
;     float mloc = fmaxf(Sc[0], Sc[1]);
; #pragma unroll
;     for (int i = 2; i < 16; ++i) mloc = fmaxf(mloc, Sc[i]);
;     mloc = max_x32(mloc);
;     const bool first = (key0 == 0);
;     if (__any(mloc > 8.f) || first) {
;         const float m_new = (mloc > 8.f || first) ? __builtin_bit_cast(float, f2bf(m_run + mloc) << 16) : m_run;
;         const float delta = m_new - m_run, alpha = __builtin_amdgcn_exp2f(-delta);
;         l_run *= alpha;
; #pragma unroll
;         for (int d = 0; d < 4; ++d)
; #pragma unroll
;             for (int i = 0; i < 16; ++i) O[d][i] *= alpha;
; #pragma unroll
;         for (int i = 0; i < 16; ++i) Sc[i] -= delta;
;         m_run = m_new;
;         mfrag[0] = hi ? (short)0 : (short)(f2bf(-m_new));
;     }
; #pragma unroll
;     for (int i = 0; i < 16; ++i) Sn[i] = 0.f;
;     Sn = MFMA32(onefrag, mfrag, Sn);
; #pragma unroll
;     for (int ks = 0; ks < 4; ++ks) {
;         const bf16x8 a0 = *(LAS const bf16x8*)(Kn + ka + (((2 * ks + hi) ^ kx) << 4));
;         Sn = MFMA32(a0, qf[ks], Sn);
;     }
;     float ls = 0.f;
; #pragma unroll
;     for (int i = 0; i < 16; ++i) { Sc[i] = __builtin_amdgcn_exp2f(Sc[i]); ls += Sc[i]; }
;     l_run += ls;
; #pragma unroll
;     for (int kk = 0; kk < 2; ++kk) {
;         if (kk == 1) __builtin_amdgcn_sched_barrier(0);
;         const bf16x8 pb = pack8(Sc, kk);
; #pragma unroll
;         for (int d = 0; d < 4; ++d) {
;             LAS const unsigned char* p = Vc + va + kk * 4096 + (((2 * d + blk) ^ vx) << 5);
;             const s16x4 lo = vtr(p), hi4 = vtr(p + 2048);
;             const bf16x8 a = __builtin_shufflevector(lo, hi4, 0, 1, 2, 3, 4, 5, 6, 7);
;             O[d] = MFMA32(a, pb, O[d]);
;         }
;     }
.Lda_h1_body:
	ds_read_b64_tr_b16 v[136:137], v156 offset:49152
	ds_read_b64_tr_b16 v[138:139], v156 offset:51200
	v_exp_f32_e32 v64, v64
	v_exp_f32_e32 v65, v65
	v_exp_f32_e32 v66, v66
	v_mfma_f32_32x32x16_bf16 v[80:95], v[240:243], v[168:171], v[120:135]
	ds_read_b64_tr_b16 v[140:141], v157 offset:49152
	ds_read_b64_tr_b16 v[142:143], v157 offset:51200
	ds_read_b64_tr_b16 v[144:145], v158 offset:49152
	ds_read_b64_tr_b16 v[146:147], v158 offset:51200
	v_exp_f32_e32 v67, v67
	v_exp_f32_e32 v68, v68
	v_exp_f32_e32 v69, v69
	v_add_f32_e32 v188, v64, v65
	v_mfma_f32_32x32x16_bf16 v[80:95], v[244:247], v[172:175], v[80:95]
	ds_read_b64_tr_b16 v[148:149], v159 offset:49152
	ds_read_b64_tr_b16 v[150:151], v159 offset:51200
	ds_read_b64_tr_b16 v[96:97], v156 offset:53248
	ds_read_b64_tr_b16 v[98:99], v156 offset:55296
	v_exp_f32_e32 v70, v70
	v_exp_f32_e32 v71, v71
	v_cvt_pk_bf16_f32 v196, v64, v65
	v_add_f32_e32 v188, v188, v66
	v_cvt_pk_bf16_f32 v197, v66, v67
	v_add_f32_e32 v188, v188, v67
	v_mfma_f32_32x32x16_bf16 v[80:95], v[248:251], v[176:179], v[80:95]
	ds_read_b64_tr_b16 v[100:101], v157 offset:53248
	ds_read_b64_tr_b16 v[102:103], v157 offset:55296
	ds_read_b64_tr_b16 v[104:105], v158 offset:53248
	ds_read_b64_tr_b16 v[106:107], v158 offset:55296
	v_exp_f32_e32 v72, v72
	v_exp_f32_e32 v73, v73
	v_exp_f32_e32 v74, v74
	v_cvt_pk_bf16_f32 v198, v68, v69
	v_add_f32_e32 v188, v188, v68
	v_add_f32_e32 v188, v188, v69
	v_mfma_f32_32x32x16_bf16 v[80:95], v[204:207], v[180:183], v[80:95]
	ds_read_b64_tr_b16 v[108:109], v159 offset:53248
	s_waitcnt lgkmcnt(14)
	ds_read_b64_tr_b16 v[110:111], v159 offset:55296
	v_cvt_pk_bf16_f32 v199, v70, v71
	v_exp_f32_e32 v75, v75
	v_exp_f32_e32 v76, v76
	v_exp_f32_e32 v77, v77
	v_add_f32_e32 v188, v188, v70
	v_add_f32_e32 v188, v188, v71
	s_waitcnt lgkmcnt(14)
	v_mfma_f32_32x32x16_bf16 v[48:63], v[136:139], v[196:199], v[48:63]
	ds_read_b128 v[240:243], v152 offset:8192
	v_exp_f32_e32 v78, v78
	v_exp_f32_e32 v79, v79
	v_cvt_pk_bf16_f32 v200, v72, v73
	v_add_f32_e32 v189, v72, v73
	v_cvt_pk_bf16_f32 v201, v74, v75
	v_add_f32_e32 v189, v189, v74
	s_waitcnt lgkmcnt(13)
	v_mfma_f32_32x32x16_bf16 v[32:47], v[140:143], v[196:199], v[32:47]
	ds_read_b128 v[244:247], v153 offset:8192
	v_cvt_pk_bf16_f32 v202, v76, v77
	v_add_f32_e32 v189, v189, v75
	v_add_f32_e32 v189, v189, v76
	v_cvt_pk_bf16_f32 v203, v78, v79
	v_add_f32_e32 v189, v189, v77
	s_waitcnt lgkmcnt(12)
	v_mfma_f32_32x32x16_bf16 v[16:31], v[144:147], v[196:199], v[16:31]
	ds_read_b128 v[248:251], v154 offset:8192
	v_add_f32_e32 v189, v189, v78
	v_add_f32_e32 v165, v165, v188
	v_add_f32_e32 v189, v189, v79
	s_waitcnt lgkmcnt(11)
	v_mfma_f32_32x32x16_bf16 v[0:15], v[148:151], v[196:199], v[0:15]
	ds_read_b128 v[204:207], v155 offset:8192
	v_add_f32_e32 v165, v165, v189
	v_max3_f32 v166, v80, v81, v82
	v_max3_f32 v166, v166, v83, v84
	s_waitcnt lgkmcnt(10)
	v_mfma_f32_32x32x16_bf16 v[48:63], v[96:99], v[200:203], v[48:63]
	v_max3_f32 v166, v166, v85, v86
	v_max3_f32 v166, v166, v87, v88
	v_max3_f32 v166, v166, v89, v90
	s_waitcnt lgkmcnt(8)
	v_mfma_f32_32x32x16_bf16 v[32:47], v[100:103], v[200:203], v[32:47]
	v_max3_f32 v166, v166, v91, v92
	v_max3_f32 v166, v166, v93, v94
	v_max_f32_e32 v166, v166, v95
	v_cmp_lt_f32_e32 vcc, s92, v166
	s_xor_b32 s14, s20, 0x8000
	s_add_i32 s14, s14, s23
	s_mov_b32 s15, m0
	s_add_i32 m0, s14, 0xc000
	s_nop 0
	global_load_lds_dwordx4 v211, s[12:13]
	s_add_i32 m0, s14, 0xe000
	s_add_u32 s4, s12, 0x60000
	s_addc_u32 s5, s13, 0
	s_waitcnt lgkmcnt(6)
	v_mfma_f32_32x32x16_bf16 v[16:31], v[104:107], v[200:203], v[16:31]
	global_load_lds_dwordx4 v211, s[4:5]
	s_mov_b32 m0, s15
	s_waitcnt lgkmcnt(4)
	v_mfma_f32_32x32x16_bf16 v[0:15], v[108:111], v[200:203], v[0:15]
	s_cbranch_vccnz .Lda_h1_resc
.Lda_h1_done:
	ds_read_b64_tr_b16 v[136:137], v156 offset:57344
	ds_read_b64_tr_b16 v[138:139], v156 offset:59392
	v_exp_f32_e32 v80, v80
	v_exp_f32_e32 v81, v81
	v_exp_f32_e32 v82, v82
	s_waitcnt lgkmcnt(5)
	v_mfma_f32_32x32x16_bf16 v[64:79], v[240:243], v[168:171], v[120:135]
	ds_read_b64_tr_b16 v[140:141], v157 offset:57344
	ds_read_b64_tr_b16 v[142:143], v157 offset:59392
	ds_read_b64_tr_b16 v[144:145], v158 offset:57344
	ds_read_b64_tr_b16 v[146:147], v158 offset:59392
	v_exp_f32_e32 v83, v83
	v_exp_f32_e32 v84, v84
	v_exp_f32_e32 v85, v85
	v_add_f32_e32 v188, v80, v81
	s_waitcnt lgkmcnt(8)
	v_mfma_f32_32x32x16_bf16 v[64:79], v[244:247], v[172:175], v[64:79]
	ds_read_b64_tr_b16 v[148:149], v159 offset:57344
	ds_read_b64_tr_b16 v[150:151], v159 offset:59392
	ds_read_b64_tr_b16 v[96:97], v156 offset:61440
	ds_read_b64_tr_b16 v[98:99], v156 offset:63488
	v_exp_f32_e32 v86, v86
	v_exp_f32_e32 v87, v87
	v_cvt_pk_bf16_f32 v196, v80, v81
	v_add_f32_e32 v188, v188, v82
	v_cvt_pk_bf16_f32 v197, v82, v83
	v_add_f32_e32 v188, v188, v83
	s_waitcnt lgkmcnt(11)
	v_mfma_f32_32x32x16_bf16 v[64:79], v[248:251], v[176:179], v[64:79]
	ds_read_b64_tr_b16 v[100:101], v157 offset:61440
	ds_read_b64_tr_b16 v[102:103], v157 offset:63488
	ds_read_b64_tr_b16 v[104:105], v158 offset:61440
	ds_read_b64_tr_b16 v[106:107], v158 offset:63488
	v_exp_f32_e32 v88, v88
	v_exp_f32_e32 v89, v89
	v_exp_f32_e32 v90, v90
	v_cvt_pk_bf16_f32 v198, v84, v85
	v_add_f32_e32 v188, v188, v84
	v_add_f32_e32 v188, v188, v85
	s_waitcnt lgkmcnt(14)
	v_mfma_f32_32x32x16_bf16 v[64:79], v[204:207], v[180:183], v[64:79]
	ds_read_b64_tr_b16 v[108:109], v159 offset:61440
	s_waitcnt lgkmcnt(14)
	ds_read_b64_tr_b16 v[110:111], v159 offset:63488
	v_cvt_pk_bf16_f32 v199, v86, v87
	v_exp_f32_e32 v91, v91
	v_exp_f32_e32 v92, v92
	v_exp_f32_e32 v93, v93
	v_add_f32_e32 v188, v188, v86
	v_add_f32_e32 v188, v188, v87
	s_waitcnt lgkmcnt(14)
; #define LAS __attribute__((address_space(3)))
; template <bool TAIL> ...
;     ...
;     float mloc = fmaxf(Sc[0], Sc[1]);
; #pragma unroll
;     for (int i = 2; i < 16; ++i) mloc = fmaxf(mloc, Sc[i]);
;     mloc = max_x32(mloc);
;     const bool first = (key0 == 0);
;     if (__any(mloc > 8.f) || first) {
;         const float m_new = (mloc > 8.f || first) ? __builtin_bit_cast(float, f2bf(m_run + mloc) << 16) : m_run;
;         const float delta = m_new - m_run, alpha = __builtin_amdgcn_exp2f(-delta);
;         l_run *= alpha;
; #pragma unroll
;         for (int d = 0; d < 4; ++d)
; #pragma unroll
;             for (int i = 0; i < 16; ++i) O[d][i] *= alpha;
; #pragma unroll
;         for (int i = 0; i < 16; ++i) Sc[i] -= delta;
;         m_run = m_new;
;         mfrag[0] = hi ? (short)0 : (short)(f2bf(-m_new));
;     }
; #pragma unroll
;     for (int i = 0; i < 16; ++i) Sn[i] = 0.f;
;     Sn = MFMA32(onefrag, mfrag, Sn);
; #pragma unroll
;     for (int ks = 0; ks < 4; ++ks) {
;         const bf16x8 a0 = *(LAS const bf16x8*)(Kn + ka + (((2 * ks + hi) ^ kx) << 4));
;         Sn = MFMA32(a0, qf[ks], Sn);
;     }
;     float ls = 0.f;
; #pragma unroll
;     for (int i = 0; i < 16; ++i) { Sc[i] = __builtin_amdgcn_exp2f(Sc[i]); ls += Sc[i]; }
;     l_run += ls;
; #pragma unroll
;     for (int kk = 0; kk < 2; ++kk) {
;         if (kk == 1) __builtin_amdgcn_sched_barrier(0);
;         const bf16x8 pb = pack8(Sc, kk);
; #pragma unroll
;         for (int d = 0; d < 4; ++d) {
;             LAS const unsigned char* p = Vc + va + kk * 4096 + (((2 * d + blk) ^ vx) << 5);
;             const s16x4 lo = vtr(p), hi4 = vtr(p + 2048);
;             const bf16x8 a = __builtin_shufflevector(lo, hi4, 0, 1, 2, 3, 4, 5, 6, 7);
;             O[d] = MFMA32(a, pb, O[d]);
;         }
;     }
; __device__ __forceinline__ void flash_map(f32x16 (&O)[4], LAS unsigned char* lds, const bf16* QKV, int qcol, int kcol, int vcol, int qb, int w, int lane, int tid) {
;     ...
;         const int buf = kt & 1;
;         const bool more = kt + 1 < nkt;
;         if (kt + 2 < nkt) DMA_K(kt + 2, kb2);
;         LAS const unsigned char* Kc = lds + kb0; LAS const unsigned char* Vb = lds + buf * 32768;
;         if (kt < nmain) {
;             flash_half<false>(O, S0, S1, m_run, l_run, mfrag, onefrag, qf, Kc + 4096, Vb, ka, kx, va, vx, blk, hi, kt * KT, qrow, qmin);
;             if (more) DMA_VH(kt + 1, buf ^ 1, 0);
	v_mfma_f32_32x32x16_bf16 v[48:63], v[136:139], v[196:199], v[48:63]
	ds_read_b128 v[240:243], v152 offset:12288
	v_exp_f32_e32 v94, v94
	v_exp_f32_e32 v95, v95
	v_cvt_pk_bf16_f32 v200, v88, v89
	v_add_f32_e32 v189, v88, v89
	v_cvt_pk_bf16_f32 v201, v90, v91
	v_add_f32_e32 v189, v189, v90
	s_waitcnt lgkmcnt(13)
	v_mfma_f32_32x32x16_bf16 v[32:47], v[140:143], v[196:199], v[32:47]
	ds_read_b128 v[244:247], v153 offset:12288
	v_cvt_pk_bf16_f32 v202, v92, v93
	v_add_f32_e32 v189, v189, v91
	v_add_f32_e32 v189, v189, v92
	v_cvt_pk_bf16_f32 v203, v94, v95
	v_add_f32_e32 v189, v189, v93
	s_waitcnt lgkmcnt(12)
	v_mfma_f32_32x32x16_bf16 v[16:31], v[144:147], v[196:199], v[16:31]
	ds_read_b128 v[248:251], v154 offset:12288
	v_add_f32_e32 v189, v189, v94
	v_add_f32_e32 v165, v165, v188
	v_add_f32_e32 v189, v189, v95
	s_waitcnt lgkmcnt(11)
	v_mfma_f32_32x32x16_bf16 v[0:15], v[148:151], v[196:199], v[0:15]
	ds_read_b128 v[204:207], v155 offset:12288
	v_add3_u32 v152, s16, v224, v225
	v_add3_u32 v153, s16, v224, v226
	v_add3_u32 v154, s16, v224, v227
	v_add3_u32 v155, s16, v224, v228
	v_add_u32_e32 v156, 0x8000, v156
	v_add_u32_e32 v157, 0x8000, v157
	v_add_u32_e32 v158, 0x8000, v158
	v_add_u32_e32 v159, 0x8000, v159
	v_add_f32_e32 v165, v165, v189
	v_max3_f32 v166, v64, v65, v66
	v_max3_f32 v166, v166, v67, v68
	s_waitcnt lgkmcnt(10)
	v_mfma_f32_32x32x16_bf16 v[48:63], v[96:99], v[200:203], v[48:63]
	v_max3_f32 v166, v166, v69, v70
	v_max3_f32 v166, v166, v71, v72
	v_max3_f32 v166, v166, v73, v74
	s_waitcnt lgkmcnt(8)
	v_mfma_f32_32x32x16_bf16 v[32:47], v[100:103], v[200:203], v[32:47]
	v_max3_f32 v166, v166, v75, v76
	v_max3_f32 v166, v166, v77, v78
	v_max_f32_e32 v166, v166, v79
	v_cmp_lt_f32_e32 vcc, s92, v166
	s_xor_b32 s14, s20, 0x8000
	s_add_i32 s14, s14, s23
	s_mov_b32 s15, m0
	s_add_i32 m0, s14, 0x10000
	s_add_u32 s4, s12, 0xc0000
	s_addc_u32 s5, s13, 0
	global_load_lds_dwordx4 v211, s[4:5]
	s_add_i32 m0, s14, 0x12000
	s_add_u32 s4, s12, 0x120000
	s_addc_u32 s5, s13, 0
	s_waitcnt lgkmcnt(6)
	v_mfma_f32_32x32x16_bf16 v[16:31], v[104:107], v[200:203], v[16:31]
	global_load_lds_dwordx4 v211, s[4:5]
	s_mov_b32 m0, s15
	s_waitcnt lgkmcnt(4)
	v_mfma_f32_32x32x16_bf16 v[0:15], v[108:111], v[200:203], v[0:15]
	s_cbranch_vccnz .Lda_h2_resc
.Lda_h2_done:
	ds_read_b64_tr_b16 v[136:137], v156 offset:32768
	ds_read_b64_tr_b16 v[138:139], v156 offset:34816
	v_exp_f32_e32 v64, v64
	v_exp_f32_e32 v65, v65
	v_exp_f32_e32 v66, v66
	s_waitcnt lgkmcnt(5)
	v_mfma_f32_32x32x16_bf16 v[80:95], v[240:243], v[168:171], v[120:135]
	ds_read_b64_tr_b16 v[140:141], v157 offset:32768
	ds_read_b64_tr_b16 v[142:143], v157 offset:34816
	ds_read_b64_tr_b16 v[144:145], v158 offset:32768
	ds_read_b64_tr_b16 v[146:147], v158 offset:34816
	v_exp_f32_e32 v67, v67
	v_exp_f32_e32 v68, v68
	v_exp_f32_e32 v69, v69
	v_add_f32_e32 v188, v64, v65
	s_waitcnt lgkmcnt(8)
	v_mfma_f32_32x32x16_bf16 v[80:95], v[244:247], v[172:175], v[80:95]
	ds_read_b64_tr_b16 v[148:149], v159 offset:32768
	ds_read_b64_tr_b16 v[150:151], v159 offset:34816
	ds_read_b64_tr_b16 v[96:97], v156 offset:36864
	ds_read_b64_tr_b16 v[98:99], v156 offset:38912
	v_exp_f32_e32 v70, v70
	v_exp_f32_e32 v71, v71
	v_cvt_pk_bf16_f32 v196, v64, v65
	v_add_f32_e32 v188, v188, v66
	v_cvt_pk_bf16_f32 v197, v66, v67
	v_add_f32_e32 v188, v188, v67
	s_waitcnt lgkmcnt(11)
	v_mfma_f32_32x32x16_bf16 v[80:95], v[248:251], v[176:179], v[80:95]
	ds_read_b64_tr_b16 v[100:101], v157 offset:36864
	ds_read_b64_tr_b16 v[102:103], v157 offset:38912
	ds_read_b64_tr_b16 v[104:105], v158 offset:36864
	ds_read_b64_tr_b16 v[106:107], v158 offset:38912
	v_exp_f32_e32 v72, v72
	v_exp_f32_e32 v73, v73
	v_exp_f32_e32 v74, v74
	v_cvt_pk_bf16_f32 v198, v68, v69
	v_add_f32_e32 v188, v188, v68
	v_add_f32_e32 v188, v188, v69
	s_waitcnt lgkmcnt(14)
	v_mfma_f32_32x32x16_bf16 v[80:95], v[204:207], v[180:183], v[80:95]
	ds_read_b64_tr_b16 v[108:109], v159 offset:36864
	s_waitcnt lgkmcnt(14)
	ds_read_b64_tr_b16 v[110:111], v159 offset:38912
	v_cvt_pk_bf16_f32 v199, v70, v71
	v_exp_f32_e32 v75, v75
	v_exp_f32_e32 v76, v76
	v_exp_f32_e32 v77, v77
	v_add_f32_e32 v188, v188, v70
	v_add_f32_e32 v188, v188, v71
	s_waitcnt lgkmcnt(14)
	v_mfma_f32_32x32x16_bf16 v[48:63], v[136:139], v[196:199], v[48:63]
	ds_read_b128 v[240:243], v152
	v_exp_f32_e32 v78, v78
	v_exp_f32_e32 v79, v79
	v_cvt_pk_bf16_f32 v200, v72, v73
	v_add_f32_e32 v189, v72, v73
	v_cvt_pk_bf16_f32 v201, v74, v75
	v_add_f32_e32 v189, v189, v74
	s_waitcnt lgkmcnt(13)
	v_mfma_f32_32x32x16_bf16 v[32:47], v[140:143], v[196:199], v[32:47]
	ds_read_b128 v[244:247], v153
	v_cvt_pk_bf16_f32 v202, v76, v77
	v_add_f32_e32 v189, v189, v75
	v_add_f32_e32 v189, v189, v76
	v_cvt_pk_bf16_f32 v203, v78, v79
	v_add_f32_e32 v189, v189, v77
	s_waitcnt lgkmcnt(12)
	v_mfma_f32_32x32x16_bf16 v[16:31], v[144:147], v[196:199], v[16:31]
	ds_read_b128 v[248:251], v154
	v_add_f32_e32 v189, v189, v78
	v_add_f32_e32 v165, v165, v188
	v_add_f32_e32 v189, v189, v79
	s_waitcnt lgkmcnt(11)
	v_mfma_f32_32x32x16_bf16 v[0:15], v[148:151], v[196:199], v[0:15]
	ds_read_b128 v[204:207], v155
	v_add_f32_e32 v165, v165, v189
	v_max3_f32 v166, v80, v81, v82
	v_max3_f32 v166, v166, v83, v84
	s_waitcnt lgkmcnt(10)
	v_mfma_f32_32x32x16_bf16 v[48:63], v[96:99], v[200:203], v[48:63]
	v_max3_f32 v166, v166, v85, v86
	v_max3_f32 v166, v166, v87, v88
	v_max3_f32 v166, v166, v89, v90
	s_waitcnt lgkmcnt(8)
	v_mfma_f32_32x32x16_bf16 v[32:47], v[100:103], v[200:203], v[32:47]
	v_max3_f32 v166, v166, v91, v92
	v_max3_f32 v166, v166, v93, v94
	v_max_f32_e32 v166, v166, v95
	v_cmp_lt_f32_e32 vcc, s92, v166
	s_waitcnt lgkmcnt(6)
	v_mfma_f32_32x32x16_bf16 v[16:31], v[104:107], v[200:203], v[16:31]
	s_waitcnt lgkmcnt(4)
	v_mfma_f32_32x32x16_bf16 v[0:15], v[108:111], v[200:203], v[0:15]
	s_cbranch_vccnz .Lda_h3_resc
; #define LAS __attribute__((address_space(3)))
; __device__ __forceinline__ unsigned f2bf(float f) { unsigned u = __builtin_bit_cast(unsigned, f); return (u + 0x7fffu + ((u >> 16) & 1u)) >> 16; }
; __device__ __forceinline__ float max_x32(float x) { float a = x, b = x; swap_x32(a, b); return fmaxf(a, b); }
; #define MFMA32(a, b, c) __builtin_amdgcn_mfma_f32_32x32x16_bf16((a), (b), (c), 0, 0, 0)
; __device__ __forceinline__ s16x4 vtr(LAS const unsigned char* p) { return __builtin_bit_cast(s16x4, __builtin_amdgcn_ds_read_tr16_b64_v4i16((LAS v4i16_t*)p)); }
; template <bool TAIL> ...
;     ...
;     float mloc = fmaxf(Sc[0], Sc[1]);
; #pragma unroll
;     for (int i = 2; i < 16; ++i) mloc = fmaxf(mloc, Sc[i]);
;     mloc = max_x32(mloc);
;     const bool first = (key0 == 0);
;     if (__any(mloc > 8.f) || first) {
;         const float m_new = (mloc > 8.f || first) ? __builtin_bit_cast(float, f2bf(m_run + mloc) << 16) : m_run;
;         const float delta = m_new - m_run, alpha = __builtin_amdgcn_exp2f(-delta);
;         l_run *= alpha;
; #pragma unroll
;         for (int d = 0; d < 4; ++d)
; #pragma unroll
;             for (int i = 0; i < 16; ++i) O[d][i] *= alpha;
; #pragma unroll
;         for (int i = 0; i < 16; ++i) Sc[i] -= delta;
;         m_run = m_new;
;         mfrag[0] = hi ? (short)0 : (short)(f2bf(-m_new));
;     }
; #pragma unroll
;     for (int i = 0; i < 16; ++i) Sn[i] = 0.f;
;     Sn = MFMA32(onefrag, mfrag, Sn);
; #pragma unroll
;     for (int ks = 0; ks < 4; ++ks) {
;         const bf16x8 a0 = *(LAS const bf16x8*)(Kn + ka + (((2 * ks + hi) ^ kx) << 4));
;         Sn = MFMA32(a0, qf[ks], Sn);
;     }
;     float ls = 0.f;
; #pragma unroll
;     for (int i = 0; i < 16; ++i) { Sc[i] = __builtin_amdgcn_exp2f(Sc[i]); ls += Sc[i]; }
;     l_run += ls;
; #pragma unroll
;     for (int kk = 0; kk < 2; ++kk) {
;         if (kk == 1) __builtin_amdgcn_sched_barrier(0);
;         const bf16x8 pb = pack8(Sc, kk);
; #pragma unroll
;         for (int d = 0; d < 4; ++d) {
;             LAS const unsigned char* p = Vc + va + kk * 4096 + (((2 * d + blk) ^ vx) << 5);
;             const s16x4 lo = vtr(p), hi4 = vtr(p + 2048);
;             const bf16x8 a = __builtin_shufflevector(lo, hi4, 0, 1, 2, 3, 4, 5, 6, 7);
;             O[d] = MFMA32(a, pb, O[d]);
;         }
;     }
.Lda_h3_done:
	ds_read_b64_tr_b16 v[136:137], v156 offset:40960
	ds_read_b64_tr_b16 v[138:139], v156 offset:43008
	v_exp_f32_e32 v80, v80
	v_exp_f32_e32 v81, v81
	v_exp_f32_e32 v82, v82
	s_waitcnt lgkmcnt(5)
	v_mfma_f32_32x32x16_bf16 v[64:79], v[240:243], v[168:171], v[120:135]
	ds_read_b64_tr_b16 v[140:141], v157 offset:40960
	ds_read_b64_tr_b16 v[142:143], v157 offset:43008
	ds_read_b64_tr_b16 v[144:145], v158 offset:40960
	ds_read_b64_tr_b16 v[146:147], v158 offset:43008
	v_exp_f32_e32 v83, v83
	v_exp_f32_e32 v84, v84
	v_exp_f32_e32 v85, v85
	v_add_f32_e32 v188, v80, v81
	s_waitcnt lgkmcnt(8)
	v_mfma_f32_32x32x16_bf16 v[64:79], v[244:247], v[172:175], v[64:79]
	ds_read_b64_tr_b16 v[148:149], v159 offset:40960
	ds_read_b64_tr_b16 v[150:151], v159 offset:43008
	ds_read_b64_tr_b16 v[96:97], v156 offset:45056
	ds_read_b64_tr_b16 v[98:99], v156 offset:47104
	v_exp_f32_e32 v86, v86
	v_exp_f32_e32 v87, v87
	v_cvt_pk_bf16_f32 v196, v80, v81
	v_add_f32_e32 v188, v188, v82
	v_cvt_pk_bf16_f32 v197, v82, v83
	v_add_f32_e32 v188, v188, v83
	s_waitcnt lgkmcnt(11)
	v_mfma_f32_32x32x16_bf16 v[64:79], v[248:251], v[176:179], v[64:79]
	ds_read_b64_tr_b16 v[100:101], v157 offset:45056
	ds_read_b64_tr_b16 v[102:103], v157 offset:47104
	ds_read_b64_tr_b16 v[104:105], v158 offset:45056
	ds_read_b64_tr_b16 v[106:107], v158 offset:47104
	v_exp_f32_e32 v88, v88
	v_exp_f32_e32 v89, v89
	v_exp_f32_e32 v90, v90
	v_cvt_pk_bf16_f32 v198, v84, v85
	v_add_f32_e32 v188, v188, v84
	v_add_f32_e32 v188, v188, v85
	s_waitcnt lgkmcnt(14)
	v_mfma_f32_32x32x16_bf16 v[64:79], v[204:207], v[180:183], v[64:79]
	ds_read_b64_tr_b16 v[108:109], v159 offset:45056
	s_waitcnt lgkmcnt(14)
	ds_read_b64_tr_b16 v[110:111], v159 offset:47104
	v_cvt_pk_bf16_f32 v199, v86, v87
	v_exp_f32_e32 v91, v91
	v_exp_f32_e32 v92, v92
	v_exp_f32_e32 v93, v93
	v_add_f32_e32 v188, v188, v86
	v_add_f32_e32 v188, v188, v87
	s_waitcnt lgkmcnt(14)
	v_mfma_f32_32x32x16_bf16 v[48:63], v[136:139], v[196:199], v[48:63]
	ds_read_b128 v[240:243], v152 offset:4096
	v_exp_f32_e32 v94, v94
	v_exp_f32_e32 v95, v95
	v_cvt_pk_bf16_f32 v200, v88, v89
	v_add_f32_e32 v189, v88, v89
	v_cvt_pk_bf16_f32 v201, v90, v91
	v_add_f32_e32 v189, v189, v90
	s_waitcnt lgkmcnt(13)
	v_mfma_f32_32x32x16_bf16 v[32:47], v[140:143], v[196:199], v[32:47]
	ds_read_b128 v[244:247], v153 offset:4096
	v_cvt_pk_bf16_f32 v202, v92, v93
	v_add_f32_e32 v189, v189, v91
	v_add_f32_e32 v189, v189, v92
	v_cvt_pk_bf16_f32 v203, v94, v95
	v_add_f32_e32 v189, v189, v93
	s_waitcnt lgkmcnt(12)
	v_mfma_f32_32x32x16_bf16 v[16:31], v[144:147], v[196:199], v[16:31]
	ds_read_b128 v[248:251], v154 offset:4096
	v_add_f32_e32 v189, v189, v94
	v_add_f32_e32 v165, v165, v188
	v_add_f32_e32 v189, v189, v95
	s_waitcnt lgkmcnt(11)
	v_mfma_f32_32x32x16_bf16 v[0:15], v[148:151], v[196:199], v[0:15]
	ds_read_b128 v[204:207], v155 offset:4096
	v_add_f32_e32 v165, v165, v189
	v_max3_f32 v166, v64, v65, v66
	v_max3_f32 v166, v166, v67, v68
	s_waitcnt lgkmcnt(10)
	v_mfma_f32_32x32x16_bf16 v[48:63], v[96:99], v[200:203], v[48:63]
	v_max3_f32 v166, v166, v69, v70
	v_max3_f32 v166, v166, v71, v72
	v_max3_f32 v166, v166, v73, v74
	s_waitcnt lgkmcnt(8)
	v_mfma_f32_32x32x16_bf16 v[32:47], v[100:103], v[200:203], v[32:47]
	v_max3_f32 v166, v166, v75, v76
	v_max3_f32 v166, v166, v77, v78
	v_max_f32_e32 v166, v166, v79
	v_cmp_lt_f32_e32 vcc, s92, v166
	s_waitcnt lgkmcnt(6)
	v_mfma_f32_32x32x16_bf16 v[16:31], v[104:107], v[200:203], v[16:31]
	s_waitcnt lgkmcnt(4)
	v_mfma_f32_32x32x16_bf16 v[0:15], v[108:111], v[200:203], v[0:15]
	s_cbranch_vccnz .Lda_h4_resc

; __device__ __forceinline__ unsigned f2bf(float f) { unsigned u = __builtin_bit_cast(unsigned, f); return (u + 0x7fffu + ((u >> 16) & 1u)) >> 16; }
; __device__ __forceinline__ float max_x32(float x) { float a = x, b = x; swap_x32(a, b); return fmaxf(a, b); }
; template <bool TAIL> ...
;     ...
;     mloc = max_x32(mloc);
;     const bool first = (key0 == 0);
;     if (__any(mloc > 8.f) || first) {
;         const float m_new = (mloc > 8.f || first) ? __builtin_bit_cast(float, f2bf(m_run + mloc) << 16) : m_run;
;         const float delta = m_new - m_run, alpha = __builtin_amdgcn_exp2f(-delta);
;         l_run *= alpha;
; #pragma unroll
;         for (int d = 0; d < 4; ++d)
; #pragma unroll
;             for (int i = 0; i < 16; ++i) O[d][i] *= alpha;
; #pragma unroll
;         for (int i = 0; i < 16; ++i) Sc[i] -= delta;
;         m_run = m_new;
;         mfrag[0] = hi ? (short)0 : (short)(f2bf(-m_new));
.Lda_h1_resc:
	v_mov_b32_e32 v239, v166
	s_nop 1
	v_permlane32_swap_b32 v166, v239
	s_nop 0
	v_max_f32_e32 v166, v166, v239
	v_cmp_lt_f32_e64 s[14:15], s92, v166
	s_nop 3
	v_mov_b32_e32 v136, v238
	s_and_saveexec_b64 s[4:5], s[14:15]
	v_add_f32_e32 v136, v238, v166
	v_bfe_u32 v137, v136, 16, 1
	v_add3_u32 v136, v136, v137, s93
	v_and_b32_e32 v136, 0xffff0000, v136
	s_or_b64 exec, exec, s[4:5]
	v_sub_f32_e32 v138, v136, v238
	v_xor_b32_e32 v137, 0x80000000, v136
	v_exp_f32_e64 v140, -v138
	v_mov_b32_e32 v120, v137
	v_mov_b32_e32 v121, v137
	v_mov_b32_e32 v122, v137
	v_mov_b32_e32 v123, v137
	v_mov_b32_e32 v124, v137
	v_mov_b32_e32 v125, v137
	v_mov_b32_e32 v126, v137
	v_mov_b32_e32 v127, v137
	v_mov_b32_e32 v128, v137
	v_mov_b32_e32 v129, v137
	v_mov_b32_e32 v130, v137
	v_mov_b32_e32 v131, v137
	v_mov_b32_e32 v132, v137
	v_mov_b32_e32 v133, v137
	v_mov_b32_e32 v134, v137
	v_mov_b32_e32 v135, v137
	v_pk_add_f32 v[80:81], v[80:81], v[138:139] op_sel_hi:[1,0] neg_lo:[0,1] neg_hi:[0,1]
	v_pk_add_f32 v[82:83], v[82:83], v[138:139] op_sel_hi:[1,0] neg_lo:[0,1] neg_hi:[0,1]
	v_pk_add_f32 v[84:85], v[84:85], v[138:139] op_sel_hi:[1,0] neg_lo:[0,1] neg_hi:[0,1]
	v_pk_add_f32 v[86:87], v[86:87], v[138:139] op_sel_hi:[1,0] neg_lo:[0,1] neg_hi:[0,1]
	v_pk_add_f32 v[88:89], v[88:89], v[138:139] op_sel_hi:[1,0] neg_lo:[0,1] neg_hi:[0,1]
	v_pk_add_f32 v[90:91], v[90:91], v[138:139] op_sel_hi:[1,0] neg_lo:[0,1] neg_hi:[0,1]
	v_pk_add_f32 v[92:93], v[92:93], v[138:139] op_sel_hi:[1,0] neg_lo:[0,1] neg_hi:[0,1]
	v_pk_add_f32 v[94:95], v[94:95], v[138:139] op_sel_hi:[1,0] neg_lo:[0,1] neg_hi:[0,1]
	v_bfe_u32 v142, v137, 16, 1
	v_add3_u32 v137, v137, v142, s93
	v_lshrrev_b32_e32 v137, 16, v137
	v_cndmask_b32_e64 v137, 0, v137, s[0:1]
	v_bfi_b32 v184, s94, v137, v184
	v_mul_f32_e32 v165, v165, v140
	v_pk_mul_f32 v[62:63], v[62:63], v[140:141] op_sel_hi:[1,0]
	v_pk_mul_f32 v[60:61], v[60:61], v[140:141] op_sel_hi:[1,0]
	v_pk_mul_f32 v[58:59], v[58:59], v[140:141] op_sel_hi:[1,0]
	v_pk_mul_f32 v[56:57], v[56:57], v[140:141] op_sel_hi:[1,0]
	v_pk_mul_f32 v[54:55], v[54:55], v[140:141] op_sel_hi:[1,0]
	v_pk_mul_f32 v[52:53], v[52:53], v[140:141] op_sel_hi:[1,0]
	v_pk_mul_f32 v[50:51], v[50:51], v[140:141] op_sel_hi:[1,0]
	v_pk_mul_f32 v[48:49], v[48:49], v[140:141] op_sel_hi:[1,0]
	v_pk_mul_f32 v[46:47], v[46:47], v[140:141] op_sel_hi:[1,0]
	v_pk_mul_f32 v[44:45], v[44:45], v[140:141] op_sel_hi:[1,0]
	v_pk_mul_f32 v[42:43], v[42:43], v[140:141] op_sel_hi:[1,0]
	v_pk_mul_f32 v[40:41], v[40:41], v[140:141] op_sel_hi:[1,0]
	v_pk_mul_f32 v[38:39], v[38:39], v[140:141] op_sel_hi:[1,0]
	v_pk_mul_f32 v[36:37], v[36:37], v[140:141] op_sel_hi:[1,0]
	v_pk_mul_f32 v[34:35], v[34:35], v[140:141] op_sel_hi:[1,0]
	v_pk_mul_f32 v[32:33], v[32:33], v[140:141] op_sel_hi:[1,0]
	v_pk_mul_f32 v[30:31], v[30:31], v[140:141] op_sel_hi:[1,0]
	v_pk_mul_f32 v[28:29], v[28:29], v[140:141] op_sel_hi:[1,0]
	v_pk_mul_f32 v[26:27], v[26:27], v[140:141] op_sel_hi:[1,0]
	v_pk_mul_f32 v[24:25], v[24:25], v[140:141] op_sel_hi:[1,0]
	v_pk_mul_f32 v[22:23], v[22:23], v[140:141] op_sel_hi:[1,0]
	v_pk_mul_f32 v[20:21], v[20:21], v[140:141] op_sel_hi:[1,0]
	v_pk_mul_f32 v[18:19], v[18:19], v[140:141] op_sel_hi:[1,0]
	v_pk_mul_f32 v[16:17], v[16:17], v[140:141] op_sel_hi:[1,0]
	v_pk_mul_f32 v[14:15], v[14:15], v[140:141] op_sel_hi:[1,0]
	v_pk_mul_f32 v[12:13], v[12:13], v[140:141] op_sel_hi:[1,0]
	v_pk_mul_f32 v[10:11], v[10:11], v[140:141] op_sel_hi:[1,0]
	v_pk_mul_f32 v[8:9], v[8:9], v[140:141] op_sel_hi:[1,0]
	v_pk_mul_f32 v[6:7], v[6:7], v[140:141] op_sel_hi:[1,0]
	v_pk_mul_f32 v[4:5], v[4:5], v[140:141] op_sel_hi:[1,0]
	v_pk_mul_f32 v[2:3], v[2:3], v[140:141] op_sel_hi:[1,0]
	v_pk_mul_f32 v[0:1], v[0:1], v[140:141] op_sel_hi:[1,0]
	v_mov_b32_e32 v238, v136
	s_branch .Lda_h1_done
; __device__ __forceinline__ unsigned f2bf(float f) { unsigned u = __builtin_bit_cast(unsigned, f); return (u + 0x7fffu + ((u >> 16) & 1u)) >> 16; }
; __device__ __forceinline__ float max_x32(float x) { float a = x, b = x; swap_x32(a, b); return fmaxf(a, b); }
; template <bool TAIL> ...
;     ...
;     mloc = max_x32(mloc);
;     const bool first = (key0 == 0);
;     if (__any(mloc > 8.f) || first) {
;         const float m_new = (mloc > 8.f || first) ? __builtin_bit_cast(float, f2bf(m_run + mloc) << 16) : m_run;
;         const float delta = m_new - m_run, alpha = __builtin_amdgcn_exp2f(-delta);
;         l_run *= alpha;
; #pragma unroll
;         for (int d = 0; d < 4; ++d)
; #pragma unroll
;             for (int i = 0; i < 16; ++i) O[d][i] *= alpha;
; #pragma unroll
;         for (int i = 0; i < 16; ++i) Sc[i] -= delta;
;         m_run = m_new;
;         mfrag[0] = hi ? (short)0 : (short)(f2bf(-m_new));
.Lda_h2_resc:
	v_mov_b32_e32 v239, v166
	s_nop 1
	v_permlane32_swap_b32 v166, v239
	s_nop 0
	v_max_f32_e32 v166, v166, v239
	v_cmp_lt_f32_e64 s[14:15], s92, v166
	s_nop 3
	v_mov_b32_e32 v136, v238
	s_and_saveexec_b64 s[4:5], s[14:15]
	v_add_f32_e32 v136, v238, v166
	v_bfe_u32 v137, v136, 16, 1
	v_add3_u32 v136, v136, v137, s93
	v_and_b32_e32 v136, 0xffff0000, v136
	s_or_b64 exec, exec, s[4:5]
	v_sub_f32_e32 v138, v136, v238
	v_xor_b32_e32 v137, 0x80000000, v136
	v_exp_f32_e64 v140, -v138
	v_mov_b32_e32 v120, v137
	v_mov_b32_e32 v121, v137
	v_mov_b32_e32 v122, v137
	v_mov_b32_e32 v123, v137
	v_mov_b32_e32 v124, v137
	v_mov_b32_e32 v125, v137
	v_mov_b32_e32 v126, v137
	v_mov_b32_e32 v127, v137
	v_mov_b32_e32 v128, v137
	v_mov_b32_e32 v129, v137
	v_mov_b32_e32 v130, v137
	v_mov_b32_e32 v131, v137
	v_mov_b32_e32 v132, v137
	v_mov_b32_e32 v133, v137
	v_mov_b32_e32 v134, v137
	v_mov_b32_e32 v135, v137
	v_pk_add_f32 v[64:65], v[64:65], v[138:139] op_sel_hi:[1,0] neg_lo:[0,1] neg_hi:[0,1]
	v_pk_add_f32 v[66:67], v[66:67], v[138:139] op_sel_hi:[1,0] neg_lo:[0,1] neg_hi:[0,1]
	v_pk_add_f32 v[68:69], v[68:69], v[138:139] op_sel_hi:[1,0] neg_lo:[0,1] neg_hi:[0,1]
	v_pk_add_f32 v[70:71], v[70:71], v[138:139] op_sel_hi:[1,0] neg_lo:[0,1] neg_hi:[0,1]
	v_pk_add_f32 v[72:73], v[72:73], v[138:139] op_sel_hi:[1,0] neg_lo:[0,1] neg_hi:[0,1]
	v_pk_add_f32 v[74:75], v[74:75], v[138:139] op_sel_hi:[1,0] neg_lo:[0,1] neg_hi:[0,1]
	v_pk_add_f32 v[76:77], v[76:77], v[138:139] op_sel_hi:[1,0] neg_lo:[0,1] neg_hi:[0,1]
	v_pk_add_f32 v[78:79], v[78:79], v[138:139] op_sel_hi:[1,0] neg_lo:[0,1] neg_hi:[0,1]
	v_bfe_u32 v142, v137, 16, 1
	v_add3_u32 v137, v137, v142, s93
	v_lshrrev_b32_e32 v137, 16, v137
	v_cndmask_b32_e64 v137, 0, v137, s[0:1]
	v_bfi_b32 v184, s94, v137, v184
	v_mul_f32_e32 v165, v165, v140
	v_pk_mul_f32 v[62:63], v[62:63], v[140:141] op_sel_hi:[1,0]
	v_pk_mul_f32 v[60:61], v[60:61], v[140:141] op_sel_hi:[1,0]
	v_pk_mul_f32 v[58:59], v[58:59], v[140:141] op_sel_hi:[1,0]
	v_pk_mul_f32 v[56:57], v[56:57], v[140:141] op_sel_hi:[1,0]
	v_pk_mul_f32 v[54:55], v[54:55], v[140:141] op_sel_hi:[1,0]
	v_pk_mul_f32 v[52:53], v[52:53], v[140:141] op_sel_hi:[1,0]
	v_pk_mul_f32 v[50:51], v[50:51], v[140:141] op_sel_hi:[1,0]
	v_pk_mul_f32 v[48:49], v[48:49], v[140:141] op_sel_hi:[1,0]
	v_pk_mul_f32 v[46:47], v[46:47], v[140:141] op_sel_hi:[1,0]
	v_pk_mul_f32 v[44:45], v[44:45], v[140:141] op_sel_hi:[1,0]
	v_pk_mul_f32 v[42:43], v[42:43], v[140:141] op_sel_hi:[1,0]
	v_pk_mul_f32 v[40:41], v[40:41], v[140:141] op_sel_hi:[1,0]
	v_pk_mul_f32 v[38:39], v[38:39], v[140:141] op_sel_hi:[1,0]
	v_pk_mul_f32 v[36:37], v[36:37], v[140:141] op_sel_hi:[1,0]
	v_pk_mul_f32 v[34:35], v[34:35], v[140:141] op_sel_hi:[1,0]
	v_pk_mul_f32 v[32:33], v[32:33], v[140:141] op_sel_hi:[1,0]
	v_pk_mul_f32 v[30:31], v[30:31], v[140:141] op_sel_hi:[1,0]
	v_pk_mul_f32 v[28:29], v[28:29], v[140:141] op_sel_hi:[1,0]
	v_pk_mul_f32 v[26:27], v[26:27], v[140:141] op_sel_hi:[1,0]
	v_pk_mul_f32 v[24:25], v[24:25], v[140:141] op_sel_hi:[1,0]
	v_pk_mul_f32 v[22:23], v[22:23], v[140:141] op_sel_hi:[1,0]
	v_pk_mul_f32 v[20:21], v[20:21], v[140:141] op_sel_hi:[1,0]
	v_pk_mul_f32 v[18:19], v[18:19], v[140:141] op_sel_hi:[1,0]
	v_pk_mul_f32 v[16:17], v[16:17], v[140:141] op_sel_hi:[1,0]
	v_pk_mul_f32 v[14:15], v[14:15], v[140:141] op_sel_hi:[1,0]
	v_pk_mul_f32 v[12:13], v[12:13], v[140:141] op_sel_hi:[1,0]
	v_pk_mul_f32 v[10:11], v[10:11], v[140:141] op_sel_hi:[1,0]
	v_pk_mul_f32 v[8:9], v[8:9], v[140:141] op_sel_hi:[1,0]
	v_pk_mul_f32 v[6:7], v[6:7], v[140:141] op_sel_hi:[1,0]
	v_pk_mul_f32 v[4:5], v[4:5], v[140:141] op_sel_hi:[1,0]
	v_pk_mul_f32 v[2:3], v[2:3], v[140:141] op_sel_hi:[1,0]
	v_pk_mul_f32 v[0:1], v[0:1], v[140:141] op_sel_hi:[1,0]
	v_mov_b32_e32 v238, v136
	s_branch .Lda_h2_done
